# RG-LRU carry-in chain: the seven (sP,sH) LDS pairs are read up front and the fma chain stops after wave links, instead of wave dependent LDS round trips
# speedup vs baseline: 1.0087x; 1.0021x over previous
; __device__ __forceinline__ float bf2f(bf16_t v) { return __uint_as_float(((unsigned)v) << 16); }
; template <int K> __device__ __forceinline__ float swz(float v) { return __int_as_float(__builtin_amdgcn_ds_swizzle(__float_as_int(v), (K << 10) | 0x1f)); }
; #define LASP __attribute__((address_space(3)))
; __device__ __forceinline__ void p3_lru2(int l, unsigned char* smem, int item) {
;     ...
;             float lgv[8];
; #pragma unroll
;             for (int e = 0; e < 8; ++e) { const int o = wave * 8 + e, tl = dir ? 63 - o : o;
;                 lgv[e] = bf2f(U[(size_t)(base + t0 + tl) * NINP + OLG + hd * 64 + lane]); }
;             __syncthreads();
;             { f32x4_t ga[4];
; #pragma unroll
;               for (int rg = 0; rg < 4; ++rg) ga[rg] = (f32x4_t){0.f, 0.f, 0.f, 0.f};
; #pragma unroll
;               for (int kk = 0; kk < 2; ++kk)
; #pragma unroll
;                   for (int rg = 0; rg < 4; ++rg) {
;                       const bf16x8_t xa = *(const LASP bf16x8_t*)(ls + O_XS + (rg * 16 + fr) * 144 + (kk * 32 + fq * 8) * 2);
;                       ga[rg] = __builtin_amdgcn_mfma_f32_16x16x32_bf16(xa, wf[kk], ga[rg], 0, 0, 0);
;                   }
;               const bool lo = fr < 8;
; #pragma unroll
;               for (int rg = 0; rg < 4; ++rg) {
;                   const float r0 = swz<8>(lo ? ga[rg][2] : ga[rg][0]), r1 = swz<8>(lo ? ga[rg][3] : ga[rg][1]);
; #pragma unroll
;                   for (int jj = 0; jj < 2; ++jj) {
;                       const float rcv = jj ? r1 : r0;
;                       const float gA_ = lo ? ga[rg][jj] : rcv, gX_ = lo ? rcv : ga[rg][2 + jj];
;                       const int tl = rg * 16 + fq * 4 + (lo ? jj : 2 + jj);
;                       const float sa = __builtin_amdgcn_rcpf(1.0f + __builtin_amdgcn_exp2f(-(gA_ + ba_) * LOG2E));
;                       const float sx = __builtin_amdgcn_rcpf(1.0f + __builtin_amdgcn_exp2f(-(gX_ + bx_) * LOG2E));
;                       const float la = -8.0f * sa * sp;
;                       const float a = __builtin_amdgcn_exp2f(la * LOG2E), mult = __builtin_amdgcn_sqrtf(one_minus_exp(2.0f * la));
;                       Aa[tl * 64 + chl] = a; Uu[tl * 64 + chl] = mult * sx * xcf[tl * 64 + chl];
;                   }
;               } }
.LBB0_770:
	s_not_b32 s2, s5
	s_add_i32 s16, s13, s2
	s_and_b64 s[2:3], s[40:41], exec
	s_cselect_b32 s2, s5, s16
	s_lshl_b32 s2, s2, 6
	s_add_i32 s5, s2, s12
	v_add_u32_e32 v135, s5, v102
	v_mad_i64_i32 v[2:3], s[2:3], v135, s90, v[88:89]
	v_add_u32_e32 v134, s5, v103
	global_load_ushort v136, v[2:3], off offset:3648
	v_mad_i64_i32 v[2:3], s[2:3], v134, s90, v[88:89]
	v_add_u32_e32 v133, s5, v104
	global_load_ushort v137, v[2:3], off offset:3648
	v_mad_i64_i32 v[2:3], s[2:3], v133, s90, v[88:89]
	v_add_u32_e32 v132, s5, v105
	global_load_ushort v138, v[2:3], off offset:3648
	v_mad_i64_i32 v[2:3], s[2:3], v132, s90, v[88:89]
	v_add_u32_e32 v131, s5, v106
	global_load_ushort v139, v[2:3], off offset:3648
	v_mad_i64_i32 v[2:3], s[2:3], v131, s90, v[88:89]
	v_add_u32_e32 v130, s5, v107
	global_load_ushort v140, v[2:3], off offset:3648
	v_mad_i64_i32 v[2:3], s[2:3], v130, s90, v[88:89]
	v_add_u32_e32 v129, s5, v108
	global_load_ushort v141, v[2:3], off offset:3648
	v_mad_i64_i32 v[2:3], s[2:3], v129, s90, v[88:89]
	v_add_u32_e32 v1, s5, v109
	global_load_ushort v142, v[2:3], off offset:3648
	v_mad_i64_i32 v[2:3], s[2:3], v1, s90, v[88:89]
	global_load_ushort v143, v[2:3], off offset:3648
	s_waitcnt lgkmcnt(0)
	s_barrier
	ds_read_b128 v[76:79], v128 offset:4608
	s_waitcnt lgkmcnt(0)
	v_mfma_f32_16x16x32_bf16 v[156:159], v[76:79], v[44:47], 0
	ds_read_b128 v[76:79], v128 offset:6912
	ds_read_b128 v[68:71], v128
	ds_read_b128 v[72:75], v128 offset:2304
	s_waitcnt lgkmcnt(2)
	v_mfma_f32_16x16x32_bf16 v[160:163], v[76:79], v[44:47], 0
	ds_read_b128 v[76:79], v128 offset:64
	s_waitcnt lgkmcnt(2)
	v_mfma_f32_16x16x32_bf16 v[68:71], v[68:71], v[44:47], 0
	s_waitcnt lgkmcnt(0)
	v_mfma_f32_16x16x32_bf16 v[80:83], v[76:79], v[48:51], v[68:71]
	s_nop 5
	ds_read_b128 v[68:71], v128 offset:2368
	v_mfma_f32_16x16x32_bf16 v[72:75], v[72:75], v[44:47], 0
	v_cndmask_b32_e64 v2, v80, v82, s[38:39]
	ds_swizzle_b32 v3, v2 offset:swizzle(SWAP,8)
	v_cndmask_b32_e64 v2, v81, v83, s[38:39]
	s_waitcnt lgkmcnt(1)
	v_mfma_f32_16x16x32_bf16 v[76:79], v[68:71], v[48:51], v[72:75]
	ds_read_b128 v[68:71], v128 offset:4672
	s_waitcnt lgkmcnt(1)
	v_cndmask_b32_e64 v80, v3, v80, s[38:39]
	v_add_f32_e32 v80, v93, v80
	v_mul_f32_e32 v80, 0xbfb8aa3b, v80
	s_waitcnt lgkmcnt(0)
	v_mfma_f32_16x16x32_bf16 v[72:75], v[68:71], v[48:51], v[156:159]
	ds_read_b128 v[68:71], v128 offset:6976
	v_exp_f32_e32 v80, v80
	ds_swizzle_b32 v2, v2 offset:swizzle(SWAP,8)
	s_waitcnt lgkmcnt(1)
	v_mfma_f32_16x16x32_bf16 v[68:71], v[68:71], v[48:51], v[160:163]
	v_add_f32_e32 v80, 1.0, v80
	v_rcp_f32_e32 v80, v80
	s_nop 0
	v_mul_f32_e32 v80, 0xc1000000, v80
	v_mul_f32_e32 v80, v95, v80
	v_add_f32_e32 v145, v80, v80
	v_cmp_nlt_f32_e32 vcc, s92, v145
	s_and_saveexec_b64 s[2:3], vcc
	s_xor_b64 s[2:3], exec, s[2:3]
	v_mul_f32_e32 v144, 0x3fb8aa3b, v145
	v_exp_f32_e32 v144, v144
	s_nop 0
	v_sub_f32_e32 v144, 1.0, v144
	s_andn2_saveexec_b64 s[2:3], s[2:3]
	v_fmamk_f32 v144, v145, 0x39500d01, v210
	v_fmaak_f32 v144, v145, v144, 0x3c088889
	v_fmaak_f32 v144, v145, v144, 0x3d2aaaab
	v_fmaak_f32 v144, v145, v144, 0x3e2aaaab
	v_fma_f32 v144, v145, v144, 0.5
	v_fma_f32 v144, v145, v144, 1.0
	v_mul_f32_e64 v144, v144, -v145
	s_or_b64 exec, exec, s[2:3]
	v_cndmask_b32_e64 v3, v82, v3, s[38:39]
	v_add_f32_e32 v3, v94, v3
	v_mul_f32_e32 v3, 0xbfb8aa3b, v3
	s_waitcnt lgkmcnt(0)
	v_cndmask_b32_e64 v81, v2, v81, s[38:39]
	v_exp_f32_e32 v3, v3
	v_add_f32_e32 v81, v93, v81
	v_mul_f32_e32 v81, 0xbfb8aa3b, v81
	v_exp_f32_e32 v81, v81
	v_add_f32_e32 v3, 1.0, v3
	v_rcp_f32_e32 v3, v3
	v_sqrt_f32_e32 v82, v144
	ds_read_b32 v144, v122 offset:9216
	v_mul_f32_e32 v80, 0x3fb8aa3b, v80
	v_add_f32_e32 v81, 1.0, v81
	v_exp_f32_e32 v80, v80
	v_rcp_f32_e32 v81, v81
	v_mul_f32_e32 v3, v3, v82
	s_waitcnt lgkmcnt(0)
	v_mul_f32_e32 v3, v3, v144
	ds_write2st64_b32 v122, v80, v3 offset0:100 offset1:164
	v_mul_f32_e32 v3, 0xc1000000, v81
	v_mul_f32_e32 v3, v95, v3
	v_add_f32_e32 v81, v3, v3
	v_cmp_nlt_f32_e32 vcc, s92, v81
	s_and_saveexec_b64 s[2:3], vcc
	s_xor_b64 s[2:3], exec, s[2:3]
	v_mul_f32_e32 v80, 0x3fb8aa3b, v81
	v_exp_f32_e32 v80, v80
	s_nop 0
	v_sub_f32_e32 v80, 1.0, v80
	s_andn2_saveexec_b64 s[2:3], s[2:3]
	v_fmamk_f32 v80, v81, 0x39500d01, v210
	v_fmaak_f32 v80, v81, v80, 0x3c088889
	v_fmaak_f32 v80, v81, v80, 0x3d2aaaab
	v_fmaak_f32 v80, v81, v80, 0x3e2aaaab
	v_fma_f32 v80, v81, v80, 0.5
	v_fma_f32 v80, v81, v80, 1.0
	v_mul_f32_e64 v80, v80, -v81
	s_or_b64 exec, exec, s[2:3]
	v_cndmask_b32_e64 v2, v83, v2, s[38:39]
	v_add_f32_e32 v2, v94, v2
	v_mul_f32_e32 v2, 0xbfb8aa3b, v2
	v_exp_f32_e32 v2, v2
	v_sqrt_f32_e32 v80, v80
	v_mul_f32_e32 v3, 0x3fb8aa3b, v3
	v_exp_f32_e32 v3, v3
	v_add_f32_e32 v2, 1.0, v2
	v_rcp_f32_e32 v2, v2
	s_nop 0
	v_mul_f32_e32 v2, v2, v80
	ds_read_b32 v80, v110 offset:9216
	s_waitcnt lgkmcnt(0)
	v_mul_f32_e32 v2, v2, v80
	ds_write2st64_b32 v110, v3, v2 offset0:100 offset1:164
	v_cndmask_b32_e64 v2, v76, v78, s[38:39]
	ds_swizzle_b32 v3, v2 offset:swizzle(SWAP,8)
	v_cndmask_b32_e64 v2, v77, v79, s[38:39]
	ds_swizzle_b32 v2, v2 offset:swizzle(SWAP,8)
	s_waitcnt lgkmcnt(1)
	v_cndmask_b32_e64 v76, v3, v76, s[38:39]
	v_add_f32_e32 v76, v93, v76
	v_mul_f32_e32 v76, 0xbfb8aa3b, v76
	v_exp_f32_e32 v76, v76
	s_nop 0
	v_add_f32_e32 v76, 1.0, v76
	v_rcp_f32_e32 v76, v76
	s_nop 0
	v_mul_f32_e32 v76, 0xc1000000, v76
	v_mul_f32_e32 v76, v95, v76
	v_add_f32_e32 v81, v76, v76
	v_cmp_nlt_f32_e32 vcc, s92, v81
	s_and_saveexec_b64 s[2:3], vcc
	s_xor_b64 s[2:3], exec, s[2:3]
	v_mul_f32_e32 v80, 0x3fb8aa3b, v81
	v_exp_f32_e32 v80, v80
	s_nop 0
	v_sub_f32_e32 v80, 1.0, v80
	s_andn2_saveexec_b64 s[2:3], s[2:3]
	v_fmamk_f32 v80, v81, 0x39500d01, v210
	v_fmaak_f32 v80, v81, v80, 0x3c088889
	v_fmaak_f32 v80, v81, v80, 0x3d2aaaab
	v_fmaak_f32 v80, v81, v80, 0x3e2aaaab
	v_fma_f32 v80, v81, v80, 0.5
	v_fma_f32 v80, v81, v80, 1.0
	v_mul_f32_e64 v80, v80, -v81
	s_or_b64 exec, exec, s[2:3]
	v_cndmask_b32_e64 v3, v78, v3, s[38:39]
	v_add_f32_e32 v3, v94, v3
	v_mul_f32_e32 v3, 0xbfb8aa3b, v3
	s_waitcnt lgkmcnt(0)
; template <int K> __device__ __forceinline__ float swz(float v) { return __int_as_float(__builtin_amdgcn_ds_swizzle(__float_as_int(v), (K << 10) | 0x1f)); }
; __device__ __forceinline__ void p3_lru2(int l, unsigned char* smem, int item) {
;     ...
;               const bool lo = fr < 8;
; #pragma unroll
;               for (int rg = 0; rg < 4; ++rg) {
;                   const float r0 = swz<8>(lo ? ga[rg][2] : ga[rg][0]), r1 = swz<8>(lo ? ga[rg][3] : ga[rg][1]);
; #pragma unroll
;                   for (int jj = 0; jj < 2; ++jj) {
;                       const float rcv = jj ? r1 : r0;
;                       const float gA_ = lo ? ga[rg][jj] : rcv, gX_ = lo ? rcv : ga[rg][2 + jj];
;                       const int tl = rg * 16 + fq * 4 + (lo ? jj : 2 + jj);
;                       const float sa = __builtin_amdgcn_rcpf(1.0f + __builtin_amdgcn_exp2f(-(gA_ + ba_) * LOG2E));
;                       const float sx = __builtin_amdgcn_rcpf(1.0f + __builtin_amdgcn_exp2f(-(gX_ + bx_) * LOG2E));
;                       const float la = -8.0f * sa * sp;
;                       const float a = __builtin_amdgcn_exp2f(la * LOG2E), mult = __builtin_amdgcn_sqrtf(one_minus_exp(2.0f * la));
;                       Aa[tl * 64 + chl] = a; Uu[tl * 64 + chl] = mult * sx * xcf[tl * 64 + chl];
;                   }
;               } }
;             __syncthreads();
	v_cndmask_b32_e64 v77, v2, v77, s[38:39]
	v_exp_f32_e32 v3, v3
	v_add_f32_e32 v77, v93, v77
	v_mul_f32_e32 v77, 0xbfb8aa3b, v77
	v_exp_f32_e32 v77, v77
	v_add_f32_e32 v3, 1.0, v3
	v_rcp_f32_e32 v3, v3
	v_sqrt_f32_e32 v78, v80
	ds_read_b32 v80, v123 offset:9216
	v_mul_f32_e32 v76, 0x3fb8aa3b, v76
	v_add_f32_e32 v77, 1.0, v77
	v_exp_f32_e32 v76, v76
	v_rcp_f32_e32 v77, v77
	v_mul_f32_e32 v3, v3, v78
	s_waitcnt lgkmcnt(0)
	v_mul_f32_e32 v3, v3, v80
	ds_write2st64_b32 v123, v76, v3 offset0:100 offset1:164
	v_mul_f32_e32 v3, 0xc1000000, v77
	v_mul_f32_e32 v3, v95, v3
	v_add_f32_e32 v77, v3, v3
	v_cmp_nlt_f32_e32 vcc, s92, v77
	s_and_saveexec_b64 s[2:3], vcc
	s_xor_b64 s[2:3], exec, s[2:3]
	v_mul_f32_e32 v76, 0x3fb8aa3b, v77
	v_exp_f32_e32 v76, v76
	s_nop 0
	v_sub_f32_e32 v76, 1.0, v76
	s_andn2_saveexec_b64 s[2:3], s[2:3]
	v_fmamk_f32 v76, v77, 0x39500d01, v210
	v_fmaak_f32 v76, v77, v76, 0x3c088889
	v_fmaak_f32 v76, v77, v76, 0x3d2aaaab
	v_fmaak_f32 v76, v77, v76, 0x3e2aaaab
	v_fma_f32 v76, v77, v76, 0.5
	v_fma_f32 v76, v77, v76, 1.0
	v_mul_f32_e64 v76, v76, -v77
	s_or_b64 exec, exec, s[2:3]
	v_cndmask_b32_e64 v2, v79, v2, s[38:39]
	v_add_f32_e32 v2, v94, v2
	v_mul_f32_e32 v2, 0xbfb8aa3b, v2
	v_exp_f32_e32 v2, v2
	v_sqrt_f32_e32 v76, v76
	v_mul_f32_e32 v3, 0x3fb8aa3b, v3
	v_exp_f32_e32 v3, v3
	v_add_f32_e32 v2, 1.0, v2
	v_rcp_f32_e32 v2, v2
	s_nop 0
	v_mul_f32_e32 v2, v2, v76
	ds_read_b32 v76, v111 offset:9216
	s_waitcnt lgkmcnt(0)
	v_mul_f32_e32 v2, v2, v76
	ds_write2st64_b32 v111, v3, v2 offset0:100 offset1:164
	v_cndmask_b32_e64 v2, v72, v74, s[38:39]
	ds_swizzle_b32 v3, v2 offset:swizzle(SWAP,8)
	v_cndmask_b32_e64 v2, v73, v75, s[38:39]
	ds_swizzle_b32 v2, v2 offset:swizzle(SWAP,8)
	s_waitcnt lgkmcnt(1)
	v_cndmask_b32_e64 v72, v3, v72, s[38:39]
	v_add_f32_e32 v72, v93, v72
	v_mul_f32_e32 v72, 0xbfb8aa3b, v72
	v_exp_f32_e32 v72, v72
	s_nop 0
	v_add_f32_e32 v72, 1.0, v72
	v_rcp_f32_e32 v72, v72
	s_nop 0
	v_mul_f32_e32 v72, 0xc1000000, v72
	v_mul_f32_e32 v72, v95, v72
	v_add_f32_e32 v77, v72, v72
	v_cmp_nlt_f32_e32 vcc, s92, v77
	s_and_saveexec_b64 s[2:3], vcc
	s_xor_b64 s[2:3], exec, s[2:3]
	v_mul_f32_e32 v76, 0x3fb8aa3b, v77
	v_exp_f32_e32 v76, v76
	s_nop 0
	v_sub_f32_e32 v76, 1.0, v76
	s_andn2_saveexec_b64 s[2:3], s[2:3]
	v_fmamk_f32 v76, v77, 0x39500d01, v210
	v_fmaak_f32 v76, v77, v76, 0x3c088889
	v_fmaak_f32 v76, v77, v76, 0x3d2aaaab
	v_fmaak_f32 v76, v77, v76, 0x3e2aaaab
	v_fma_f32 v76, v77, v76, 0.5
	v_fma_f32 v76, v77, v76, 1.0
	v_mul_f32_e64 v76, v76, -v77
	s_or_b64 exec, exec, s[2:3]
	v_cndmask_b32_e64 v3, v74, v3, s[38:39]
	v_add_f32_e32 v3, v94, v3
	v_mul_f32_e32 v3, 0xbfb8aa3b, v3
	s_waitcnt lgkmcnt(0)
	v_cndmask_b32_e64 v73, v2, v73, s[38:39]
	v_exp_f32_e32 v3, v3
	v_add_f32_e32 v73, v93, v73
	v_mul_f32_e32 v73, 0xbfb8aa3b, v73
	v_exp_f32_e32 v73, v73
	v_add_f32_e32 v3, 1.0, v3
	v_rcp_f32_e32 v3, v3
	v_sqrt_f32_e32 v74, v76
	ds_read_b32 v76, v124 offset:9216
	v_mul_f32_e32 v72, 0x3fb8aa3b, v72
	v_add_f32_e32 v73, 1.0, v73
	v_exp_f32_e32 v72, v72
	v_rcp_f32_e32 v73, v73
	v_mul_f32_e32 v3, v3, v74
	s_waitcnt lgkmcnt(0)
	v_mul_f32_e32 v3, v3, v76
	ds_write2st64_b32 v124, v72, v3 offset0:100 offset1:164
	v_mul_f32_e32 v3, 0xc1000000, v73
	v_mul_f32_e32 v3, v95, v3
	v_add_f32_e32 v73, v3, v3
	v_cmp_nlt_f32_e32 vcc, s92, v73
	s_and_saveexec_b64 s[2:3], vcc
	s_xor_b64 s[2:3], exec, s[2:3]
	v_mul_f32_e32 v72, 0x3fb8aa3b, v73
	v_exp_f32_e32 v72, v72
	s_nop 0
	v_sub_f32_e32 v72, 1.0, v72
	s_andn2_saveexec_b64 s[2:3], s[2:3]
	v_fmamk_f32 v72, v73, 0x39500d01, v210
	v_fmaak_f32 v72, v73, v72, 0x3c088889
	v_fmaak_f32 v72, v73, v72, 0x3d2aaaab
	v_fmaak_f32 v72, v73, v72, 0x3e2aaaab
	v_fma_f32 v72, v73, v72, 0.5
	v_fma_f32 v72, v73, v72, 1.0
	v_mul_f32_e64 v72, v72, -v73
	s_or_b64 exec, exec, s[2:3]
	v_cndmask_b32_e64 v2, v75, v2, s[38:39]
	v_add_f32_e32 v2, v94, v2
	v_mul_f32_e32 v2, 0xbfb8aa3b, v2
	v_exp_f32_e32 v2, v2
	v_sqrt_f32_e32 v72, v72
	v_mul_f32_e32 v3, 0x3fb8aa3b, v3
	v_exp_f32_e32 v3, v3
	v_add_f32_e32 v2, 1.0, v2
	v_rcp_f32_e32 v2, v2
	s_nop 0
	v_mul_f32_e32 v2, v2, v72
	ds_read_b32 v72, v112 offset:9216
	s_waitcnt lgkmcnt(0)
	v_mul_f32_e32 v2, v2, v72
	ds_write2st64_b32 v112, v3, v2 offset0:100 offset1:164
	v_cndmask_b32_e64 v2, v68, v70, s[38:39]
	ds_swizzle_b32 v3, v2 offset:swizzle(SWAP,8)
	v_cndmask_b32_e64 v2, v69, v71, s[38:39]
	ds_swizzle_b32 v2, v2 offset:swizzle(SWAP,8)
	s_waitcnt lgkmcnt(1)
	v_cndmask_b32_e64 v68, v3, v68, s[38:39]
	v_add_f32_e32 v68, v93, v68
	v_mul_f32_e32 v68, 0xbfb8aa3b, v68
	v_exp_f32_e32 v68, v68
	s_nop 0
	v_add_f32_e32 v68, 1.0, v68
	v_rcp_f32_e32 v68, v68
	s_nop 0
	v_mul_f32_e32 v68, 0xc1000000, v68
	v_mul_f32_e32 v68, v95, v68
	v_add_f32_e32 v73, v68, v68
	v_cmp_nlt_f32_e32 vcc, s92, v73
	s_and_saveexec_b64 s[2:3], vcc
	s_xor_b64 s[2:3], exec, s[2:3]
	v_mul_f32_e32 v72, 0x3fb8aa3b, v73
	v_exp_f32_e32 v72, v72
	s_nop 0
	v_sub_f32_e32 v72, 1.0, v72
	s_andn2_saveexec_b64 s[2:3], s[2:3]
	v_fmamk_f32 v72, v73, 0x39500d01, v210
	v_fmaak_f32 v72, v73, v72, 0x3c088889
	v_fmaak_f32 v72, v73, v72, 0x3d2aaaab
	v_fmaak_f32 v72, v73, v72, 0x3e2aaaab
	v_fma_f32 v72, v73, v72, 0.5
	v_fma_f32 v72, v73, v72, 1.0
	v_mul_f32_e64 v72, v72, -v73
	s_or_b64 exec, exec, s[2:3]
	v_cndmask_b32_e64 v3, v70, v3, s[38:39]
	v_add_f32_e32 v3, v94, v3
	v_mul_f32_e32 v3, 0xbfb8aa3b, v3
	s_waitcnt lgkmcnt(0)
	v_cndmask_b32_e64 v69, v2, v69, s[38:39]
	v_exp_f32_e32 v3, v3
	v_add_f32_e32 v69, v93, v69
	v_mul_f32_e32 v69, 0xbfb8aa3b, v69
	v_exp_f32_e32 v69, v69
	v_add_f32_e32 v3, 1.0, v3
	v_rcp_f32_e32 v3, v3
	v_sqrt_f32_e32 v70, v72
	ds_read_b32 v72, v125 offset:9216
	v_mul_f32_e32 v68, 0x3fb8aa3b, v68
	v_add_f32_e32 v69, 1.0, v69
	v_exp_f32_e32 v68, v68
	v_rcp_f32_e32 v69, v69
	v_mul_f32_e32 v3, v3, v70
	s_waitcnt lgkmcnt(0)
	v_mul_f32_e32 v3, v3, v72
	ds_write2st64_b32 v125, v68, v3 offset0:100 offset1:164
	v_mul_f32_e32 v3, 0xc1000000, v69
	v_mul_f32_e32 v3, v95, v3
	v_add_f32_e32 v69, v3, v3
	v_cmp_nlt_f32_e32 vcc, s92, v69
	s_and_saveexec_b64 s[2:3], vcc
	s_xor_b64 s[2:3], exec, s[2:3]
	v_mul_f32_e32 v68, 0x3fb8aa3b, v69
	v_exp_f32_e32 v68, v68
	s_nop 0
	v_sub_f32_e32 v68, 1.0, v68
	s_andn2_saveexec_b64 s[2:3], s[2:3]
	v_fmamk_f32 v68, v69, 0x39500d01, v210
	v_fmaak_f32 v68, v69, v68, 0x3c088889
	v_fmaak_f32 v68, v69, v68, 0x3d2aaaab
	v_fmaak_f32 v68, v69, v68, 0x3e2aaaab
	v_fma_f32 v68, v69, v68, 0.5
	v_fma_f32 v68, v69, v68, 1.0
	v_mul_f32_e64 v68, v68, -v69
	s_or_b64 exec, exec, s[2:3]
	v_cndmask_b32_e64 v2, v71, v2, s[38:39]
	v_add_f32_e32 v2, v94, v2
	v_mul_f32_e32 v2, 0xbfb8aa3b, v2
	v_exp_f32_e32 v2, v2
	v_sqrt_f32_e32 v68, v68
	ds_read_b32 v69, v113 offset:9216
	v_mul_f32_e32 v3, 0x3fb8aa3b, v3
	v_add_f32_e32 v2, 1.0, v2
	v_rcp_f32_e32 v2, v2
	v_exp_f32_e32 v3, v3
	v_mul_f32_e32 v2, v2, v68
	s_waitcnt lgkmcnt(0)
	v_mul_f32_e32 v2, v2, v69
	ds_write2st64_b32 v113, v3, v2 offset0:100 offset1:164
	s_waitcnt lgkmcnt(0)
	s_barrier
; __device__ __forceinline__ bf16_t f2bf(float f) { return (bf16_t)(pk2(f, 0.0f) & 0xffffu); }
; __device__ __forceinline__ void p3_lru2(int l, unsigned char* smem, int item) {
;     ...
;             float hl[8], pp[8];
;             { float h = 0.f, p = 1.f;
; #pragma unroll
;               for (int e = 0; e < 8; ++e) { const int o = wave * 8 + e, tl = dir ? 63 - o : o;
;                   const float a = Aa[tl * 64 + lane], u = Uu[tl * 64 + lane];
;                   h = a * h + u; p *= a; hl[e] = h; pp[e] = p; }
;               sP[wave * 64 + lane] = p; sH[wave * 64 + lane] = h; }
;             __syncthreads();
;             { float cin = hc[par * 64 + lane];
;               for (int s2 = 0; s2 < wave; ++s2) cin = sP[s2 * 64 + lane] * cin + sH[s2 * 64 + lane];
; #pragma unroll
;               for (int e = 0; e < 8; ++e) { const int o = wave * 8 + e, tl = dir ? 63 - o : o;
;                   const float h = hl[e] + pp[e] * cin;
;                   const size_t row = (size_t)(base + t0 + tl);
;                   const float g = lgv[e];
;                   const float gl = g * __builtin_amdgcn_rcpf(1.0f + __builtin_amdgcn_exp2f(-2.3022082f * (g + 0.044715f * g * g * g)));
;                   O[row * OW + 768 + dir * 256 + hd * 64 + lane] = f2bf(gl * h);
;                   if (e == 7 && wave == 7) hc[(par ^ 1) * 64 + lane] = h; } }
;             par ^= 1;
	ds_read2st64_b32 v[80:81], v114 offset0:100 offset1:164
	ds_read2st64_b32 v[78:79], v115 offset0:100 offset1:164
	ds_read2st64_b32 v[76:77], v116 offset0:100 offset1:164
	ds_read2st64_b32 v[74:75], v117 offset0:100 offset1:164
	ds_read2st64_b32 v[72:73], v118 offset0:100 offset1:164
	s_waitcnt lgkmcnt(4)
	v_fma_f32 v82, 0, v80, v81
	ds_read2st64_b32 v[70:71], v119 offset0:100 offset1:164
	s_waitcnt lgkmcnt(4)
	v_mul_f32_e32 v81, v80, v78
	v_fmac_f32_e32 v79, v82, v78
	ds_read2st64_b32 v[68:69], v120 offset0:100 offset1:164
	s_waitcnt lgkmcnt(4)
	v_mul_f32_e32 v78, v81, v76
	v_fmac_f32_e32 v77, v79, v76
	ds_read2st64_b32 v[2:3], v121 offset0:100 offset1:164
	s_waitcnt lgkmcnt(4)
	v_mul_f32_e32 v76, v78, v74
	v_fmac_f32_e32 v75, v77, v74
	s_waitcnt lgkmcnt(3)
	v_mul_f32_e32 v74, v76, v72
	v_fmac_f32_e32 v73, v75, v72
	s_waitcnt lgkmcnt(2)
	v_mul_f32_e32 v72, v74, v70
	v_fmac_f32_e32 v71, v73, v70
	s_waitcnt lgkmcnt(1)
	v_mul_f32_e32 v70, v72, v68
	v_fmac_f32_e32 v69, v71, v68
	s_waitcnt lgkmcnt(0)
	v_mul_f32_e32 v68, v70, v2
	v_fmac_f32_e32 v3, v69, v2
	v_lshl_add_u32 v2, s10, 8, v101
	ds_write2st64_b32 v96, v68, v3 offset0:228 offset1:236
	s_waitcnt lgkmcnt(0)
	s_barrier
	ds_read_b32 v2, v2 offset:62464
	ds_read2st64_b32 v[156:157], v126 offset1:8
	ds_read2st64_b32 v[158:159], v126 offset0:1 offset1:9
	ds_read2st64_b32 v[160:161], v126 offset0:2 offset1:10
	ds_read2st64_b32 v[162:163], v126 offset0:3 offset1:11
	ds_read2st64_b32 v[164:165], v126 offset0:4 offset1:12
	ds_read2st64_b32 v[166:167], v126 offset0:5 offset1:13
	ds_read2st64_b32 v[168:169], v126 offset0:6 offset1:14
	v_readfirstlane_b32 s99, v92
	s_cmp_lt_u32 s99, 1
	s_cbranch_scc1 .Llru_carry_done
	s_waitcnt lgkmcnt(6)
	v_fma_f32 v2, v2, v156, v157
	s_cmp_lt_u32 s99, 2
	s_cbranch_scc1 .Llru_carry_done
	s_waitcnt lgkmcnt(5)
	v_fma_f32 v2, v2, v158, v159
	s_cmp_lt_u32 s99, 3
	s_cbranch_scc1 .Llru_carry_done
	s_waitcnt lgkmcnt(4)
	v_fma_f32 v2, v2, v160, v161
	s_cmp_lt_u32 s99, 4
	s_cbranch_scc1 .Llru_carry_done
	s_waitcnt lgkmcnt(3)
	v_fma_f32 v2, v2, v162, v163
	s_cmp_lt_u32 s99, 5
	s_cbranch_scc1 .Llru_carry_done
	s_waitcnt lgkmcnt(2)
	v_fma_f32 v2, v2, v164, v165
	s_cmp_lt_u32 s99, 6
	s_cbranch_scc1 .Llru_carry_done
	s_waitcnt lgkmcnt(1)
	v_fma_f32 v2, v2, v166, v167
	s_cmp_lt_u32 s99, 7
	s_cbranch_scc1 .Llru_carry_done
	s_waitcnt lgkmcnt(0)
	v_fma_f32 v2, v2, v168, v169
.Llru_carry_done:
.LBB0_806:
	s_waitcnt vmcnt(7)
	v_lshlrev_b32_e32 v83, 16, v136
	s_waitcnt lgkmcnt(0)
	v_fmac_f32_e32 v82, v80, v2
	v_mul_f32_e32 v80, 0x3d372713, v83
	v_mul_f32_e32 v80, v80, v83
	v_fma_f32 v80, v80, v83, v83
	v_mul_f32_e32 v80, 0xc0135761, v80
	v_exp_f32_e32 v80, v80
	s_waitcnt vmcnt(6)
	v_lshlrev_b32_e32 v136, 16, v137
	s_waitcnt vmcnt(5)
	v_lshlrev_b32_e32 v137, 16, v138
	s_waitcnt vmcnt(4)
	v_lshlrev_b32_e32 v138, 16, v139
	v_add_f32_e32 v80, 1.0, v80
	v_rcp_f32_e32 v80, v80
	v_fmac_f32_e32 v77, v78, v2
	v_mul_f32_e32 v78, 0x3d372713, v137
	s_waitcnt vmcnt(3)
	v_lshlrev_b32_e32 v139, 16, v140
	v_mul_f32_e32 v80, v80, v83
	v_mul_f32_e32 v80, v80, v82
	v_cvt_pk_bf16_f32 v80, v80, s0
	v_mad_i64_i32 v[82:83], s[2:3], v135, s93, v[84:85]
	global_store_short v[82:83], v80, off
	v_mul_f32_e32 v80, 0x3d372713, v136
	v_mul_f32_e32 v80, v80, v136
	v_fma_f32 v80, v80, v136, v136
	v_mul_f32_e32 v78, v78, v137
	v_fmac_f32_e32 v75, v76, v2
	v_mul_f32_e32 v76, 0x3d372713, v138
	s_waitcnt vmcnt(3)
	v_lshlrev_b32_e32 v140, 16, v141
	v_mul_f32_e32 v80, 0xc0135761, v80
	v_fma_f32 v78, v78, v137, v137
	v_mul_f32_e32 v76, v76, v138
	v_fmac_f32_e32 v73, v74, v2
	v_mul_f32_e32 v74, 0x3d372713, v139
	s_waitcnt vmcnt(2)
	v_lshlrev_b32_e32 v141, 16, v142
	v_exp_f32_e32 v80, v80
	v_mul_f32_e32 v78, 0xc0135761, v78
	v_fma_f32 v76, v76, v138, v138
	v_mul_f32_e32 v74, v74, v139
	v_fmac_f32_e32 v71, v72, v2
	v_mul_f32_e32 v72, 0x3d372713, v140
	s_waitcnt vmcnt(1)
	v_lshlrev_b32_e32 v142, 16, v143
	v_exp_f32_e32 v78, v78
	v_mul_f32_e32 v76, 0xc0135761, v76
	v_fma_f32 v74, v74, v139, v139
	v_mul_f32_e32 v72, v72, v140
	v_fmac_f32_e32 v69, v70, v2
	v_mul_f32_e32 v70, 0x3d372713, v141
	v_fmac_f32_e32 v79, v81, v2
	v_exp_f32_e32 v76, v76
	v_mul_f32_e32 v74, 0xc0135761, v74
	v_fma_f32 v72, v72, v140, v140
	v_mul_f32_e32 v70, v70, v141
	v_fmac_f32_e32 v3, v68, v2
	v_mul_f32_e32 v2, 0x3d372713, v142
	v_exp_f32_e32 v74, v74
	v_mul_f32_e32 v72, 0xc0135761, v72
	v_fma_f32 v70, v70, v141, v141
	v_mul_f32_e32 v2, v2, v142
	v_add_f32_e32 v80, 1.0, v80
	v_exp_f32_e32 v72, v72
	v_mul_f32_e32 v70, 0xc0135761, v70
	v_fma_f32 v2, v2, v142, v142
	v_rcp_f32_e32 v80, v80
	v_add_f32_e32 v78, 1.0, v78
	v_exp_f32_e32 v70, v70
	v_mul_f32_e32 v2, 0xc0135761, v2
	v_rcp_f32_e32 v78, v78
	v_add_f32_e32 v76, 1.0, v76
	v_exp_f32_e32 v2, v2
	v_rcp_f32_e32 v76, v76
	v_add_f32_e32 v74, 1.0, v74
	v_rcp_f32_e32 v74, v74
	v_add_f32_e32 v72, 1.0, v72
	v_mul_f32_e32 v80, v80, v136
	v_rcp_f32_e32 v72, v72
	v_add_f32_e32 v70, 1.0, v70
	v_mul_f32_e32 v79, v80, v79
	v_mul_f32_e32 v78, v78, v137
	v_rcp_f32_e32 v70, v70
	v_add_f32_e32 v2, 1.0, v2
	v_cvt_pk_bf16_f32 v79, v79, s0
	v_mad_i64_i32 v[80:81], s[2:3], v134, s93, v[84:85]
	v_mul_f32_e32 v77, v78, v77
	v_mul_f32_e32 v76, v76, v138
	v_rcp_f32_e32 v2, v2
	global_store_short v[80:81], v79, off
	v_cvt_pk_bf16_f32 v77, v77, s0
	v_mad_i64_i32 v[78:79], s[2:3], v133, s93, v[84:85]
	v_mul_f32_e32 v75, v76, v75
	v_mul_f32_e32 v74, v74, v139
	global_store_short v[78:79], v77, off
	v_cvt_pk_bf16_f32 v75, v75, s0
	v_mad_i64_i32 v[76:77], s[2:3], v132, s93, v[84:85]
	v_mul_f32_e32 v73, v74, v73
	v_mul_f32_e32 v72, v72, v140
	global_store_short v[76:77], v75, off
	v_cvt_pk_bf16_f32 v73, v73, s0
	v_mad_i64_i32 v[74:75], s[2:3], v131, s93, v[84:85]
	v_mul_f32_e32 v71, v72, v71
	v_mul_f32_e32 v70, v70, v141
	global_store_short v[74:75], v73, off
	v_cvt_pk_bf16_f32 v71, v71, s0
	v_mad_i64_i32 v[72:73], s[2:3], v130, s93, v[84:85]
	v_mul_f32_e32 v69, v70, v69
	v_mul_f32_e32 v2, v2, v142
	global_store_short v[72:73], v71, off
	v_cvt_pk_bf16_f32 v69, v69, s0
	v_mad_i64_i32 v[70:71], s[2:3], v129, s93, v[84:85]
	v_mul_f32_e32 v2, v2, v3
	global_store_short v[70:71], v69, off
	v_cvt_pk_bf16_f32 v2, v2, s0
	v_mad_i64_i32 v[68:69], s[2:3], v1, s93, v[84:85]
	global_store_short v[68:69], v2, off
	s_and_saveexec_b64 s[2:3], s[44:45]
	s_lshl_b32 s5, s10, 6
	v_bitop3_b32 v1, s5, 64, v97 bitop3:0x36
	v_lshl_add_u32 v1, v1, 2, 0
	ds_write_b32 v1, v3 offset:62464
	s_or_b64 exec, exec, s[2:3]
	s_xor_b32 s10, s10, 1
	s_cmp_eq_u32 s27, s13
	s_cbranch_scc1 .LBB0_750
	s_mov_b32 s5, s27
	s_branch .LBB0_760
